# waves 4-7: COMMIT arithmetic moved to stage S (results held in v124-v135), only 3 LDS writes in stage Y; tail drain vmcnt(0) when last ISSUE skipped
# baseline (speedup 1.0000x reference)
.LBB0_403:
	s_or_b64 exec, exec, s[2:3]
	s_waitcnt lgkmcnt(0)
	s_barrier
	v_add_u32_e32 v191, 0x17d00, v177
	s_and_saveexec_b64 s[2:3], s[56:57]
	s_cbranch_execz .Lis0c
	s_cmp_gt_u32 s36, 62
	s_cbranch_scc1 .Lcp0
	s_waitcnt vmcnt(5)
	v_lshlrev_b32_e32 v136, 16, v1
	v_and_b32_e32 v137, 0xffff0000, v1
	v_pk_mul_f32 v[124:125], v[102:103], v[136:137]
	s_waitcnt vmcnt(2)
	v_lshlrev_b32_e32 v126, 16, v3
	s_waitcnt vmcnt(1)
	v_pk_mul_f32 v[124:125], v[108:109], v[124:125] op_sel_hi:[0,1]
	v_and_b32_e32 v127, 0xffff0000, v3
	v_lshlrev_b32_e32 v130, 16, v4
	v_and_b32_e32 v131, 0xffff0000, v4
	v_pk_add_f32 v[128:129], v[130:131], -1.0 op_sel_hi:[1,0]
	v_pk_mul_f32 v[130:131], v[130:131], v[124:125] neg_lo:[0,1] neg_hi:[0,1]
	v_pk_fma_f32 v[128:129], v[104:105], v[128:129], 1.0 op_sel_hi:[1,1,0]
	s_nop 0
	v_pk_mul_f32 v[128:129], v[128:129], v[136:137]
	v_lshlrev_b32_e32 v132, 16, v0
	v_and_b32_e32 v133, 0xffff0000, v0
	v_lshlrev_b32_e32 v134, 16, v2
	v_and_b32_e32 v135, 0xffff0000, v2
.Lcp0:
	s_cmp_eq_u32 s36, 0
	s_cbranch_scc1 .Lis0b
	s_cmp_gt_u32 s36, 62
	s_cbranch_scc1 .Lis0b
	s_add_i32 s24, s19, 0xffffffc0
	s_add_i32 s25, s21, 0x30
	s_and_b64 s[98:99], s[12:13], exec
	s_cselect_b32 s24, s25, s24
	v_lshl_add_u32 v194, s24, 6, v183
	v_lshlrev_b64 v[112:113], 1, v[194:195]
	v_lshl_add_u64 v[114:115], s[44:45], 0, v[112:113]
	global_load_dword v5, v[114:115], off
	v_lshl_add_u64 v[114:115], s[42:43], 0, v[112:113]
	global_load_dword v6, v[114:115], off
	v_lshl_add_u64 v[114:115], s[0:1], 0, v[112:113]
	global_load_dword v7, v[114:115], off
	v_lshl_add_u64 v[114:115], s[34:35], 0, v[112:113]
	global_load_dword v8, v[114:115], off
	v_lshl_add_u64 v[114:115], s[76:77], 0, v[112:113]
	global_load_dword v9, v[114:115], off
	v_add_u32_e32 v194, s24, v184
	v_lshl_add_u64 v[114:115], v[194:195], 2, s[40:41]
	global_load_dword v110, v[114:115], off

.LBB0_422:
	s_or_b64 exec, exec, s[2:3]
	s_cmp_lt_u32 s36, 63
	s_cselect_b64 vcc, -1, 0
	s_cmp_gt_u32 s36, 62
	s_cbranch_scc1 .LBB0_424
	s_and_b64 s[98:99], s[56:57], exec
	s_cbranch_scc0 .Lcm0_old
	ds_write2_b64 v106, v[124:125], v[126:127] offset1:32
	ds_write2_b64 v106, v[128:129], v[130:131] offset0:64 offset1:96
	ds_write2_b64 v106, v[132:133], v[134:135] offset0:128 offset1:160
	s_branch .LBB0_424
.Lcm0_old:
	s_waitcnt vmcnt(10)
	v_lshlrev_b32_e32 v22, 16, v1
	v_and_b32_e32 v23, 0xffff0000, v1
	v_pk_mul_f32 v[24:25], v[102:103], v[22:23]
	s_waitcnt vmcnt(7)
	v_lshlrev_b32_e32 v26, 16, v3
	s_waitcnt vmcnt(6)
	v_pk_mul_f32 v[24:25], v[108:109], v[24:25] op_sel_hi:[0,1]
	v_and_b32_e32 v27, 0xffff0000, v3
	ds_write2_b64 v106, v[24:25], v[26:27] offset1:32
	v_lshlrev_b32_e32 v26, 16, v4
	v_and_b32_e32 v27, 0xffff0000, v4
	v_pk_add_f32 v[28:29], v[26:27], -1.0 op_sel_hi:[1,0]
	v_pk_mul_f32 v[24:25], v[26:27], v[24:25] neg_lo:[0,1] neg_hi:[0,1]
	v_pk_fma_f32 v[28:29], v[104:105], v[28:29], 1.0 op_sel_hi:[1,1,0]
	s_nop 0
	v_pk_mul_f32 v[22:23], v[28:29], v[22:23]
	ds_write2_b64 v106, v[22:23], v[24:25] offset0:64 offset1:96
	v_lshlrev_b32_e32 v22, 16, v0
	v_and_b32_e32 v23, 0xffff0000, v0
	v_lshlrev_b32_e32 v24, 16, v2
	v_and_b32_e32 v25, 0xffff0000, v2
	ds_write2_b64 v106, v[22:23], v[24:25] offset0:128 offset1:160
.LBB0_424:
.LBB0_426:
	s_add_i32 s24, s19, -16
	s_and_b64 s[2:3], s[12:13], exec
	s_waitcnt lgkmcnt(0)
	s_barrier
	s_cselect_b32 s2, s21, s24
	s_cmpk_lt_u32 s20, 0x7f
	ds_read_b64 v[236:237], v190
	v_lshl_add_u32 v194, s2, 6, v183
	s_cselect_b64 s[2:3], -1, 0
	v_lshl_add_u64 v[238:239], v[194:195], 1, s[78:79]
	s_and_b64 s[68:69], s[54:55], s[2:3]
	s_and_saveexec_b64 s[74:75], s[54:55]
	s_cbranch_execz .Lsx1_c
	s_cmp_gt_u32 s36, 61
	s_cbranch_scc1 .Lis1aw
	s_add_i32 s24, s19, 0xffffffb0
	s_add_i32 s25, s21, 64
	s_and_b64 s[98:99], s[12:13], exec
	s_cselect_b32 s24, s25, s24
	v_lshl_add_u32 v194, s24, 6, v183
	v_lshlrev_b64 v[112:113], 1, v[194:195]
	v_lshl_add_u64 v[114:115], s[44:45], 0, v[112:113]
	global_load_dword v0, v[114:115], off
	v_lshl_add_u64 v[114:115], s[42:43], 0, v[112:113]
	global_load_dword v1, v[114:115], off
	v_lshl_add_u64 v[114:115], s[0:1], 0, v[112:113]
	global_load_dword v2, v[114:115], off
	v_lshl_add_u64 v[114:115], s[76:77], 0, v[112:113]
	global_load_dword v4, v[114:115], off
	v_lshl_add_u64 v[114:115], s[34:35], 0, v[112:113]
	global_load_dword v3, v[114:115], off
	v_add_u32_e32 v194, s24, v184
	v_lshl_add_u64 v[114:115], v[194:195], 2, s[40:41]
	global_load_dword v108, v[114:115], off
	s_branch .Lis1a
.Lis1aw:
	s_waitcnt vmcnt(0)
.Lis1a:
	s_waitcnt lgkmcnt(0)
	v_cvt_pk_bf16_f32 v240, v236, v237
	global_store_dword v[238:239], v240, off

.LBB0_432:
	s_or_b64 exec, exec, s[74:75]
	s_waitcnt lgkmcnt(0)
	s_barrier
	s_and_saveexec_b64 s[74:75], s[56:57]
	s_cbranch_execz .Lis1c
	s_cmp_gt_u32 s36, 62
	s_cbranch_scc1 .Lcp1
	s_waitcnt vmcnt(5)
	v_lshlrev_b32_e32 v136, 16, v6
	v_and_b32_e32 v137, 0xffff0000, v6
	v_pk_mul_f32 v[124:125], v[102:103], v[136:137]
	s_waitcnt vmcnt(3)
	v_lshlrev_b32_e32 v126, 16, v8
	s_waitcnt vmcnt(1)
	v_pk_mul_f32 v[124:125], v[110:111], v[124:125] op_sel_hi:[0,1]
	v_and_b32_e32 v127, 0xffff0000, v8
	v_lshlrev_b32_e32 v130, 16, v9
	v_and_b32_e32 v131, 0xffff0000, v9
	v_pk_add_f32 v[128:129], v[130:131], -1.0 op_sel_hi:[1,0]
	v_pk_mul_f32 v[130:131], v[130:131], v[124:125] neg_lo:[0,1] neg_hi:[0,1]
	v_pk_fma_f32 v[128:129], v[104:105], v[128:129], 1.0 op_sel_hi:[1,1,0]
	s_nop 0
	v_pk_mul_f32 v[128:129], v[128:129], v[136:137]
	v_lshlrev_b32_e32 v132, 16, v5
	v_and_b32_e32 v133, 0xffff0000, v5
	v_lshlrev_b32_e32 v134, 16, v7
	v_and_b32_e32 v135, 0xffff0000, v7
.Lcp1:
	s_cmp_gt_u32 s36, 61
	s_cbranch_scc1 .Lis1bw
	s_add_i32 s24, s19, 0xffffffb0
	s_add_i32 s25, s21, 64
	s_and_b64 s[98:99], s[12:13], exec
	s_cselect_b32 s24, s25, s24
	v_lshl_add_u32 v194, s24, 6, v183
	v_lshlrev_b64 v[112:113], 1, v[194:195]
	v_lshl_add_u64 v[114:115], s[44:45], 0, v[112:113]
	global_load_dword v0, v[114:115], off
	v_lshl_add_u64 v[114:115], s[42:43], 0, v[112:113]
	global_load_dword v1, v[114:115], off
	v_lshl_add_u64 v[114:115], s[0:1], 0, v[112:113]
	global_load_dword v2, v[114:115], off
	v_lshl_add_u64 v[114:115], s[76:77], 0, v[112:113]
	global_load_dword v4, v[114:115], off
	v_lshl_add_u64 v[114:115], s[34:35], 0, v[112:113]
	global_load_dword v3, v[114:115], off
	v_add_u32_e32 v194, s24, v184
	v_lshl_add_u64 v[114:115], v[194:195], 2, s[40:41]
	global_load_dword v108, v[114:115], off
	s_branch .Lis1b
.Lis1bw:
	s_waitcnt vmcnt(0)
.Lis1b:
.Lis1c:
	s_or_b64 exec, exec, s[74:75]
	s_and_saveexec_b64 s[74:75], s[48:49]
	s_cbranch_execz .LBB0_434
	s_setprio 3
	v_mov_b32_e32 v23, 0x17900
	ds_read2st64_b32 v[32:33], v191 offset0:0 offset1:1
	ds_read_b128 v[48:51], v23 offset:0
	ds_read2st64_b32 v[34:35], v191 offset0:2 offset1:3
	ds_read2st64_b32 v[36:37], v191 offset0:4 offset1:5
	ds_read_b128 v[52:55], v23 offset:16
	ds_read2st64_b32 v[38:39], v191 offset0:6 offset1:7
	ds_read2st64_b32 v[40:41], v191 offset0:8 offset1:9
	ds_read_b128 v[56:59], v23 offset:32
	ds_read2st64_b32 v[42:43], v191 offset0:10 offset1:11
	ds_read2st64_b32 v[44:45], v191 offset0:12 offset1:13
	ds_read_b128 v[60:63], v23 offset:48
	ds_read2st64_b32 v[46:47], v191 offset0:14 offset1:15
	ds_read_b128 v[64:67], v23 offset:64
	ds_read_b128 v[68:71], v23 offset:80
	ds_read_b128 v[72:75], v23 offset:96
	s_waitcnt lgkmcnt(13)
	v_fmac_f32_e32 v33, v49, v32
	s_waitcnt lgkmcnt(12)
	v_pk_fma_f32 v[34:35], v[50:51], v[32:33], v[34:35] op_sel_hi:[1,0,1]
	ds_read_b128 v[76:79], v23 offset:112
	s_waitcnt lgkmcnt(11)
	v_pk_fma_f32 v[36:37], v[52:53], v[32:33], v[36:37] op_sel_hi:[1,0,1]
	ds_read_b128 v[80:83], v23 offset:128
	ds_read_b128 v[84:87], v23 offset:144
	s_waitcnt lgkmcnt(12)
	v_pk_fma_f32 v[38:39], v[54:55], v[32:33], v[38:39] op_sel_hi:[1,0,1]
	ds_read_b128 v[88:91], v23 offset:160
	s_waitcnt lgkmcnt(11)
	v_pk_fma_f32 v[40:41], v[56:57], v[32:33], v[40:41] op_sel_hi:[1,0,1]
	ds_read_b128 v[92:95], v23 offset:176
	ds_read_b128 v[112:115], v23 offset:208
	s_waitcnt lgkmcnt(12)
	v_pk_fma_f32 v[42:43], v[58:59], v[32:33], v[42:43] op_sel_hi:[1,0,1]
	ds_read_b128 v[116:119], v23 offset:224
	s_waitcnt lgkmcnt(11)
	v_pk_fma_f32 v[44:45], v[60:61], v[32:33], v[44:45] op_sel_hi:[1,0,1]
	ds_read_b128 v[120:123], v23 offset:240
	ds_read_b128 v[124:127], v23 offset:272
	s_waitcnt lgkmcnt(12)
	v_pk_fma_f32 v[46:47], v[62:63], v[32:33], v[46:47] op_sel_hi:[1,0,1]
	ds_read_b128 v[128:131], v23 offset:288
	s_waitcnt lgkmcnt(12)
	v_pk_fma_f32 v[34:35], v[66:67], v[32:33], v[34:35] op_sel:[0,1,0] op_sel_hi:[1,1,1]
	ds_read_b128 v[132:135], v23 offset:304
	s_waitcnt lgkmcnt(12)
	v_pk_fma_f32 v[36:37], v[68:69], v[32:33], v[36:37] op_sel:[0,1,0] op_sel_hi:[1,1,1]
	ds_read_b128 v[204:207], v23 offset:336
	v_pk_fma_f32 v[38:39], v[70:71], v[32:33], v[38:39] op_sel:[0,1,0] op_sel_hi:[1,1,1]
	s_waitcnt lgkmcnt(12)
	v_pk_fma_f32 v[40:41], v[72:73], v[32:33], v[40:41] op_sel:[0,1,0] op_sel_hi:[1,1,1]
	ds_read_b128 v[208:211], v23 offset:352
	v_pk_fma_f32 v[42:43], v[74:75], v[32:33], v[42:43] op_sel:[0,1,0] op_sel_hi:[1,1,1]
	s_waitcnt lgkmcnt(12)
	v_pk_fma_f32 v[44:45], v[76:77], v[32:33], v[44:45] op_sel:[0,1,0] op_sel_hi:[1,1,1]
	ds_read_b128 v[212:215], v23 offset:368
	v_pk_fma_f32 v[46:47], v[78:79], v[32:33], v[46:47] op_sel:[0,1,0] op_sel_hi:[1,1,1]
	s_waitcnt lgkmcnt(12)
	v_fmac_f32_e32 v35, v83, v34
	ds_read_b128 v[216:219], v23 offset:400
	s_waitcnt lgkmcnt(12)
	v_pk_fma_f32 v[36:37], v[84:85], v[34:35], v[36:37] op_sel_hi:[1,0,1]
	ds_read_b128 v[228:231], v23 offset:416
	v_pk_fma_f32 v[38:39], v[86:87], v[34:35], v[38:39] op_sel_hi:[1,0,1]
	s_waitcnt lgkmcnt(12)
	v_pk_fma_f32 v[40:41], v[88:89], v[34:35], v[40:41] op_sel_hi:[1,0,1]
	ds_read_b128 v[232:235], v23 offset:432
	v_pk_fma_f32 v[42:43], v[90:91], v[34:35], v[42:43] op_sel_hi:[1,0,1]
	s_waitcnt lgkmcnt(12)
	v_pk_fma_f32 v[44:45], v[92:93], v[34:35], v[44:45] op_sel_hi:[1,0,1]
	ds_read_b128 v[48:51], v23 offset:480
	v_pk_fma_f32 v[46:47], v[94:95], v[34:35], v[46:47] op_sel_hi:[1,0,1]
	s_waitcnt lgkmcnt(12)
	v_pk_fma_f32 v[36:37], v[112:113], v[34:35], v[36:37] op_sel:[0,1,0] op_sel_hi:[1,1,1]
	ds_read_b128 v[52:55], v23 offset:496
	v_pk_fma_f32 v[38:39], v[114:115], v[34:35], v[38:39] op_sel:[0,1,0] op_sel_hi:[1,1,1]
	s_waitcnt lgkmcnt(12)
	v_pk_fma_f32 v[40:41], v[116:117], v[34:35], v[40:41] op_sel:[0,1,0] op_sel_hi:[1,1,1]
	ds_read_b128 v[56:59], v23 offset:544
	v_pk_fma_f32 v[42:43], v[118:119], v[34:35], v[42:43] op_sel:[0,1,0] op_sel_hi:[1,1,1]
	s_waitcnt lgkmcnt(12)
	v_pk_fma_f32 v[44:45], v[120:121], v[34:35], v[44:45] op_sel:[0,1,0] op_sel_hi:[1,1,1]
	ds_read_b128 v[60:63], v23 offset:560
	v_pk_fma_f32 v[46:47], v[122:123], v[34:35], v[46:47] op_sel:[0,1,0] op_sel_hi:[1,1,1]
	s_waitcnt lgkmcnt(12)
	v_fmac_f32_e32 v37, v125, v36
	ds_read_b128 v[64:67], v23 offset:608
	v_pk_fma_f32 v[38:39], v[126:127], v[36:37], v[38:39] op_sel_hi:[1,0,1]
	s_waitcnt lgkmcnt(12)
	v_pk_fma_f32 v[40:41], v[128:129], v[36:37], v[40:41] op_sel_hi:[1,0,1]
	ds_read_b128 v[68:71], v23 offset:624
	v_pk_fma_f32 v[42:43], v[130:131], v[36:37], v[42:43] op_sel_hi:[1,0,1]
	s_waitcnt lgkmcnt(12)
	v_pk_fma_f32 v[44:45], v[132:133], v[36:37], v[44:45] op_sel_hi:[1,0,1]
	ds_read_b128 v[72:75], v23 offset:672
	v_pk_fma_f32 v[46:47], v[134:135], v[36:37], v[46:47] op_sel_hi:[1,0,1]
	s_waitcnt lgkmcnt(12)
	v_pk_fma_f32 v[38:39], v[206:207], v[36:37], v[38:39] op_sel:[0,1,0] op_sel_hi:[1,1,1]
	ds_read_b128 v[76:79], v23 offset:688
	s_waitcnt lgkmcnt(12)
	v_pk_fma_f32 v[40:41], v[208:209], v[36:37], v[40:41] op_sel:[0,1,0] op_sel_hi:[1,1,1]
	ds_read_b128 v[80:83], v23 offset:752
	v_pk_fma_f32 v[42:43], v[210:211], v[36:37], v[42:43] op_sel:[0,1,0] op_sel_hi:[1,1,1]
	s_waitcnt lgkmcnt(12)
	v_pk_fma_f32 v[44:45], v[212:213], v[36:37], v[44:45] op_sel:[0,1,0] op_sel_hi:[1,1,1]
	ds_read_b128 v[84:87], v23 offset:816
	v_pk_fma_f32 v[46:47], v[214:215], v[36:37], v[46:47] op_sel:[0,1,0] op_sel_hi:[1,1,1]
	s_waitcnt lgkmcnt(12)
	v_fmac_f32_e32 v39, v219, v38
	ds_read_b128 v[88:91], v23 offset:880
	s_waitcnt lgkmcnt(12)
	v_pk_fma_f32 v[40:41], v[228:229], v[38:39], v[40:41] op_sel_hi:[1,0,1]
	ds_read_b128 v[92:95], v23 offset:944
	v_pk_fma_f32 v[42:43], v[230:231], v[38:39], v[42:43] op_sel_hi:[1,0,1]
	s_waitcnt lgkmcnt(12)
	v_pk_fma_f32 v[44:45], v[232:233], v[38:39], v[44:45] op_sel_hi:[1,0,1]
	v_pk_fma_f32 v[46:47], v[234:235], v[38:39], v[46:47] op_sel_hi:[1,0,1]
	s_waitcnt lgkmcnt(11)
	v_pk_fma_f32 v[40:41], v[48:49], v[38:39], v[40:41] op_sel:[0,1,0] op_sel_hi:[1,1,1]
	v_pk_fma_f32 v[42:43], v[50:51], v[38:39], v[42:43] op_sel:[0,1,0] op_sel_hi:[1,1,1]
	s_waitcnt lgkmcnt(10)
	v_pk_fma_f32 v[44:45], v[52:53], v[38:39], v[44:45] op_sel:[0,1,0] op_sel_hi:[1,1,1]
	v_pk_fma_f32 v[46:47], v[54:55], v[38:39], v[46:47] op_sel:[0,1,0] op_sel_hi:[1,1,1]
	s_waitcnt lgkmcnt(9)
	v_fmac_f32_e32 v41, v57, v40
	v_pk_fma_f32 v[42:43], v[58:59], v[40:41], v[42:43] op_sel_hi:[1,0,1]
	s_waitcnt lgkmcnt(8)
	v_pk_fma_f32 v[44:45], v[60:61], v[40:41], v[44:45] op_sel_hi:[1,0,1]
	v_pk_fma_f32 v[46:47], v[62:63], v[40:41], v[46:47] op_sel_hi:[1,0,1]
	s_waitcnt lgkmcnt(7)
	v_pk_fma_f32 v[42:43], v[66:67], v[40:41], v[42:43] op_sel:[0,1,0] op_sel_hi:[1,1,1]
	s_waitcnt lgkmcnt(6)
	v_pk_fma_f32 v[44:45], v[68:69], v[40:41], v[44:45] op_sel:[0,1,0] op_sel_hi:[1,1,1]
	v_pk_fma_f32 v[46:47], v[70:71], v[40:41], v[46:47] op_sel:[0,1,0] op_sel_hi:[1,1,1]
	s_waitcnt lgkmcnt(5)
	v_fmac_f32_e32 v43, v75, v42
	s_waitcnt lgkmcnt(4)
	v_pk_fma_f32 v[44:45], v[76:77], v[42:43], v[44:45] op_sel_hi:[1,0,1]
	v_pk_fma_f32 v[46:47], v[78:79], v[42:43], v[46:47] op_sel_hi:[1,0,1]
	s_waitcnt lgkmcnt(3)
	v_pk_fma_f32 v[44:45], v[80:81], v[42:43], v[44:45] op_sel:[0,1,0] op_sel_hi:[1,1,1]
	v_pk_fma_f32 v[46:47], v[82:83], v[42:43], v[46:47] op_sel:[0,1,0] op_sel_hi:[1,1,1]
	s_waitcnt lgkmcnt(2)
	v_fmac_f32_e32 v45, v85, v44
	v_pk_fma_f32 v[46:47], v[86:87], v[44:45], v[46:47] op_sel_hi:[1,0,1]
	s_waitcnt lgkmcnt(1)
	v_pk_fma_f32 v[46:47], v[90:91], v[44:45], v[46:47] op_sel:[0,1,0] op_sel_hi:[1,1,1]
	s_waitcnt lgkmcnt(0)
	v_fmac_f32_e32 v47, v95, v46
	v_cvt_pk_bf16_f32 v24, v32, v33
	v_cvt_pk_bf16_f32 v25, v34, v35
	v_cvt_pk_bf16_f32 v26, v36, v37
	v_cvt_pk_bf16_f32 v27, v38, v39
	v_cvt_pk_bf16_f32 v28, v40, v41
	v_cvt_pk_bf16_f32 v29, v42, v43
	v_cvt_pk_bf16_f32 v30, v44, v45
	v_cvt_pk_bf16_f32 v31, v46, v47
	ds_write_b128 v140, v[24:27] offset:5120
	ds_write_b128 v140, v[28:31] offset:5136
	s_setprio 0

.LBB0_451:
	s_or_b64 exec, exec, s[2:3]
	s_andn2_b64 vcc, exec, vcc
	s_cbranch_vccnz .LBB0_453
	s_and_b64 s[98:99], s[56:57], exec
	s_cbranch_scc0 .Lcm1_old
	ds_write2_b64 v107, v[124:125], v[126:127] offset1:32
	ds_write2_b64 v107, v[128:129], v[130:131] offset0:64 offset1:96
	ds_write2_b64 v107, v[132:133], v[134:135] offset0:128 offset1:160
	s_branch .LBB0_453
.Lcm1_old:
	s_waitcnt vmcnt(10)
	v_lshlrev_b32_e32 v22, 16, v6
	v_and_b32_e32 v23, 0xffff0000, v6
	v_pk_mul_f32 v[24:25], v[102:103], v[22:23]
	s_waitcnt vmcnt(8)
	v_lshlrev_b32_e32 v26, 16, v8
	s_waitcnt vmcnt(6)
	v_pk_mul_f32 v[24:25], v[110:111], v[24:25] op_sel_hi:[0,1]
	v_and_b32_e32 v27, 0xffff0000, v8
	ds_write2_b64 v107, v[24:25], v[26:27] offset1:32
	v_lshlrev_b32_e32 v26, 16, v9
	v_and_b32_e32 v27, 0xffff0000, v9
	v_pk_add_f32 v[28:29], v[26:27], -1.0 op_sel_hi:[1,0]
	v_pk_mul_f32 v[24:25], v[26:27], v[24:25] neg_lo:[0,1] neg_hi:[0,1]
	v_pk_fma_f32 v[28:29], v[104:105], v[28:29], 1.0 op_sel_hi:[1,1,0]
	s_nop 0
	v_pk_mul_f32 v[22:23], v[28:29], v[22:23]
	ds_write2_b64 v107, v[22:23], v[24:25] offset0:64 offset1:96
	v_lshlrev_b32_e32 v22, 16, v5
	v_and_b32_e32 v23, 0xffff0000, v5
	v_lshlrev_b32_e32 v24, 16, v7
	v_and_b32_e32 v25, 0xffff0000, v7
	ds_write2_b64 v107, v[22:23], v[24:25] offset0:128 offset1:160
